# saddr
# speedup vs baseline: 1.0028x; 1.0028x over previous
; #define PG8_STAGE(bufoff, gbase, voff) do { _Pragma("unroll") for (int _i = 0; _i < 2; ++_i) \
;         __builtin_amdgcn_global_load_lds((const unsigned*)((const char*)(gbase) + (voff)[_i]), (LAS unsigned*)(lds + (bufoff) + ldsw + _i * 8192), 16, 0, 0); } while (0)
; #define PG8_LDA(dst, b, h) do { _Pragma("unroll") for (int m = 0; m < 4; ++m) _Pragma("unroll") for (int k = 0; k < 2; ++k) dst[m][k] = *(const LAS bf16x8*)(lds + PG8_SA(b, h) + aoff + m * 2048 + k * 1024); } while (0)
; #define PG8_LDB(dst, b, h) do { _Pragma("unroll") for (int n = 0; n < 2; ++n) _Pragma("unroll") for (int k = 0; k < 2; ++k) dst[n][k] = *(const LAS bf16x8*)(lds + PG8_SB(b, h) + boff + n * 2048 + k * 1024); } while (0)
; #define PG8_MMA(ai, bj, At, Bt) do { __builtin_amdgcn_s_setprio(1); _Pragma("unroll") for (int m = 0; m < 4; ++m) _Pragma("unroll") for (int n = 0; n < 2; ++n) _Pragma("unroll") for (int k = 0; k < 2; ++k) \
;         acc[ai][bj][m][n] = __builtin_amdgcn_mfma_f32_16x16x32_bf16(Bt[n][k], At[m][k], acc[ai][bj][m][n], 0, 0, 0); __builtin_amdgcn_s_setprio(0); } while (0)
; #define PG8_WAIT_V(n) asm volatile("s_waitcnt vmcnt(" #n ")" ::: "memory")
; #define PG8_WAIT_L(n) asm volatile("s_waitcnt lgkmcnt(" #n ")" ::: "memory")
; #define PG8_BAR __builtin_amdgcn_s_barrier()
; #define PG8_SCHED __builtin_amdgcn_sched_barrier(0)
; template <class Epi, class Job>
; __device__ __forceinline__ void gemm_phase(LAS unsigned char* lds, const Job& S, const Epi& E) {
;     ...
;             PG8_LDB(B0, 0, 0); PG8_SCHED; PG8_LDA(At, 0, 0); PG8_STAGE(PG8_SA(1, 1), a1 + hstepA, voffA);
;             PG8_WAIT_L(8); PG8_BAR; PG8_WAIT_L(0); PG8_MMA(0, 0, At, B0); PG8_BAR; PG8_SCHED;
;             PG8_LDB(B1, 0, 1); PG8_STAGE(PG8_SB(0, 0), b2, voffB);
;             PG8_BAR; PG8_WAIT_L(0); PG8_MMA(0, 1, At, B1); PG8_BAR;
;             PG8_LDA(At, 0, 1); PG8_STAGE(PG8_SA(0, 0), a2, voffA);
;             PG8_BAR; PG8_WAIT_L(0); PG8_MMA(1, 0, At, B0); PG8_BAR; PG8_SCHED;
;             PG8_STAGE(PG8_SB(0, 1), b2 + hstepB, voffB);
;             PG8_WAIT_V(6); PG8_BAR; PG8_MMA(1, 1, At, B1); PG8_BAR;
;             PG8_LDB(B0, 1, 0); PG8_SCHED; PG8_LDA(At, 1, 0); PG8_STAGE(PG8_SA(0, 1), a2 + hstepA, voffA);
;             PG8_WAIT_L(8); PG8_BAR; PG8_WAIT_L(0); PG8_MMA(0, 0, At, B0); PG8_BAR; PG8_SCHED;
.LBB0_186:
	ds_read_b128 v[158:161], v154
	ds_read_b128 v[174:177], v154 offset:1024
	ds_read_b128 v[178:181], v154 offset:2048
	ds_read_b128 v[182:185], v154 offset:3072
	s_add_u32 s36, s28, 0xfff00080
	s_addc_u32 s37, s29, -1
	s_cmp_eq_u32 s68, 60
	s_cselect_b32 s47, s23, s37
	s_cselect_b32 s46, s22, s36
	s_cselect_b32 s37, s25, s67
	s_cselect_b32 s36, s24, s27
	s_add_i32 m0, s52, 0xc000
	ds_read_b128 v[186:189], v155
	ds_read_b128 v[190:193], v155 offset:1024
	ds_read_b128 v[194:197], v155 offset:2048
	ds_read_b128 v[198:201], v155 offset:3072
	ds_read_b128 v[202:205], v155 offset:4096
	ds_read_b128 v[206:209], v155 offset:5120
	ds_read_b128 v[210:213], v155 offset:6144
	ds_read_b128 v[214:217], v155 offset:7168
	global_load_lds_dwordx4 v144, s[28:29]
	s_add_i32 m0, s52, 0xe000
	s_nop 0
	global_load_lds_dwordx4 v146, s[28:29]
	s_waitcnt lgkmcnt(8)
	s_barrier
	s_waitcnt lgkmcnt(0)
	s_setprio 1
	s_waitcnt lgkmcnt(0)
	v_mfma_f32_16x16x32_bf16 v[124:127], v[158:161], v[186:189], v[124:127]
	v_mfma_f32_16x16x32_bf16 v[120:123], v[178:181], v[186:189], v[120:123]
	v_mfma_f32_16x16x32_bf16 v[112:115], v[158:161], v[194:197], v[112:115]
	v_mfma_f32_16x16x32_bf16 v[104:107], v[178:181], v[194:197], v[104:107]
	v_mfma_f32_16x16x32_bf16 v[100:103], v[158:161], v[202:205], v[100:103]
	v_mfma_f32_16x16x32_bf16 v[92:95], v[178:181], v[202:205], v[92:95]
	v_mfma_f32_16x16x32_bf16 v[84:87], v[158:161], v[210:213], v[84:87]
	v_mfma_f32_16x16x32_bf16 v[76:79], v[178:181], v[210:213], v[76:79]
	v_mfma_f32_16x16x32_bf16 v[124:127], v[174:177], v[190:193], v[124:127]
	v_mfma_f32_16x16x32_bf16 v[120:123], v[182:185], v[190:193], v[120:123]
	v_mfma_f32_16x16x32_bf16 v[112:115], v[174:177], v[198:201], v[112:115]
	v_mfma_f32_16x16x32_bf16 v[104:107], v[182:185], v[198:201], v[104:107]
	v_mfma_f32_16x16x32_bf16 v[100:103], v[174:177], v[206:209], v[100:103]
	v_mfma_f32_16x16x32_bf16 v[92:95], v[182:185], v[206:209], v[92:95]
	v_mfma_f32_16x16x32_bf16 v[84:87], v[174:177], v[214:217], v[84:87]
	v_mfma_f32_16x16x32_bf16 v[76:79], v[182:185], v[214:217], v[76:79]
	s_setprio 0
	s_barrier
	s_add_i32 s69, s60, s49
	s_mov_b32 m0, s69
	ds_read_b128 v[218:221], v156
	ds_read_b128 v[222:225], v156 offset:1024
	ds_read_b128 v[226:229], v156 offset:2048
	ds_read_b128 v[230:233], v156 offset:3072
	global_load_lds_dwordx4 v136, s[36:37]
	s_add_i32 m0, s69, 0x2000
	s_nop 0
	global_load_lds_dwordx4 v140, s[36:37]
	s_barrier
	s_waitcnt lgkmcnt(0)
	s_setprio 1
	s_waitcnt lgkmcnt(0)
	v_mfma_f32_16x16x32_bf16 v[116:119], v[218:221], v[186:189], v[116:119]
	v_mfma_f32_16x16x32_bf16 v[108:111], v[226:229], v[186:189], v[108:111]
	v_mfma_f32_16x16x32_bf16 v[96:99], v[218:221], v[194:197], v[96:99]
	v_mfma_f32_16x16x32_bf16 v[88:91], v[226:229], v[194:197], v[88:91]
	v_mfma_f32_16x16x32_bf16 v[80:83], v[218:221], v[202:205], v[80:83]
	v_mfma_f32_16x16x32_bf16 v[72:75], v[226:229], v[202:205], v[72:75]
	v_mfma_f32_16x16x32_bf16 v[68:71], v[218:221], v[210:213], v[68:71]
	v_mfma_f32_16x16x32_bf16 v[64:67], v[226:229], v[210:213], v[64:67]
	v_mfma_f32_16x16x32_bf16 v[116:119], v[222:225], v[190:193], v[116:119]
	v_mfma_f32_16x16x32_bf16 v[108:111], v[230:233], v[190:193], v[108:111]
	v_mfma_f32_16x16x32_bf16 v[96:99], v[222:225], v[198:201], v[96:99]
	v_mfma_f32_16x16x32_bf16 v[88:91], v[230:233], v[198:201], v[88:91]
	v_mfma_f32_16x16x32_bf16 v[80:83], v[222:225], v[206:209], v[80:83]
	v_mfma_f32_16x16x32_bf16 v[72:75], v[230:233], v[206:209], v[72:75]
	v_mfma_f32_16x16x32_bf16 v[68:71], v[222:225], v[214:217], v[68:71]
	v_mfma_f32_16x16x32_bf16 v[64:67], v[230:233], v[214:217], v[64:67]
	s_setprio 0
	s_mov_b32 m0, s52
	s_mov_b64 s[100:101], s[46:47]
	s_barrier
	ds_read_b128 v[186:189], v155 offset:16384
	ds_read_b128 v[190:193], v155 offset:17408
	ds_read_b128 v[194:197], v155 offset:18432
	ds_read_b128 v[198:201], v155 offset:19456
	ds_read_b128 v[202:205], v155 offset:20480
	ds_read_b128 v[206:209], v155 offset:21504
	ds_read_b128 v[210:213], v155 offset:22528
	ds_read_b128 v[214:217], v155 offset:23552
	global_load_lds_dwordx4 v134, s[46:47]
	s_mov_b32 m0, s53
	s_nop 0
	global_load_lds_dwordx4 v138, s[46:47]
	s_barrier
	s_waitcnt lgkmcnt(0)
	s_setprio 1
	s_waitcnt lgkmcnt(0)
	v_mfma_f32_16x16x32_bf16 v[60:63], v[158:161], v[186:189], v[60:63]
	v_mfma_f32_16x16x32_bf16 v[56:59], v[178:181], v[186:189], v[56:59]
	v_mfma_f32_16x16x32_bf16 v[52:55], v[158:161], v[194:197], v[52:55]
	v_mfma_f32_16x16x32_bf16 v[44:47], v[178:181], v[194:197], v[44:47]
	v_mfma_f32_16x16x32_bf16 v[36:39], v[158:161], v[202:205], v[36:39]
	v_mfma_f32_16x16x32_bf16 v[28:31], v[178:181], v[202:205], v[28:31]
	v_mfma_f32_16x16x32_bf16 v[20:23], v[158:161], v[210:213], v[20:23]
	v_mfma_f32_16x16x32_bf16 v[12:15], v[178:181], v[210:213], v[12:15]
	v_mfma_f32_16x16x32_bf16 v[60:63], v[174:177], v[190:193], v[60:63]
	v_mfma_f32_16x16x32_bf16 v[56:59], v[182:185], v[190:193], v[56:59]
	v_mfma_f32_16x16x32_bf16 v[52:55], v[174:177], v[198:201], v[52:55]
	v_mfma_f32_16x16x32_bf16 v[44:47], v[182:185], v[198:201], v[44:47]
	v_mfma_f32_16x16x32_bf16 v[36:39], v[174:177], v[206:209], v[36:39]
	v_mfma_f32_16x16x32_bf16 v[28:31], v[182:185], v[206:209], v[28:31]
	v_mfma_f32_16x16x32_bf16 v[20:23], v[174:177], v[214:217], v[20:23]
	v_mfma_f32_16x16x32_bf16 v[12:15], v[182:185], v[214:217], v[12:15]
	s_setprio 0
	s_barrier
	s_add_u32 s70, s36, 0x100000
	s_addc_u32 s71, s37, 0
	s_add_i32 s69, s61, s49
	s_mov_b32 m0, s69
	s_nop 0
	global_load_lds_dwordx4 v136, s[70:71]
	s_add_i32 m0, s69, 0x2000
	s_nop 0
	global_load_lds_dwordx4 v140, s[70:71]
	s_waitcnt vmcnt(6)
	s_barrier
; #define PG8_STAGE(bufoff, gbase, voff) do { _Pragma("unroll") for (int _i = 0; _i < 2; ++_i) \
;         __builtin_amdgcn_global_load_lds((const unsigned*)((const char*)(gbase) + (voff)[_i]), (LAS unsigned*)(lds + (bufoff) + ldsw + _i * 8192), 16, 0, 0); } while (0)
; #define PG8_LDA(dst, b, h) do { _Pragma("unroll") for (int m = 0; m < 4; ++m) _Pragma("unroll") for (int k = 0; k < 2; ++k) dst[m][k] = *(const LAS bf16x8*)(lds + PG8_SA(b, h) + aoff + m * 2048 + k * 1024); } while (0)
; #define PG8_LDB(dst, b, h) do { _Pragma("unroll") for (int n = 0; n < 2; ++n) _Pragma("unroll") for (int k = 0; k < 2; ++k) dst[n][k] = *(const LAS bf16x8*)(lds + PG8_SB(b, h) + boff + n * 2048 + k * 1024); } while (0)
; #define PG8_MMA(ai, bj, At, Bt) do { __builtin_amdgcn_s_setprio(1); _Pragma("unroll") for (int m = 0; m < 4; ++m) _Pragma("unroll") for (int n = 0; n < 2; ++n) _Pragma("unroll") for (int k = 0; k < 2; ++k) \
;         acc[ai][bj][m][n] = __builtin_amdgcn_mfma_f32_16x16x32_bf16(Bt[n][k], At[m][k], acc[ai][bj][m][n], 0, 0, 0); __builtin_amdgcn_s_setprio(0); } while (0)
; #define PG8_WAIT_V(n) asm volatile("s_waitcnt vmcnt(" #n ")" ::: "memory")
; #define PG8_WAIT_L(n) asm volatile("s_waitcnt lgkmcnt(" #n ")" ::: "memory")
; #define PG8_BAR __builtin_amdgcn_s_barrier()
; #define PG8_SCHED __builtin_amdgcn_sched_barrier(0)
; template <class Epi, class Job>
; __device__ __forceinline__ void gemm_phase(LAS unsigned char* lds, const Job& S, const Epi& E) {
;     ...
;             PG8_BAR; PG8_WAIT_L(0); PG8_MMA(1, 0, At, B0); PG8_BAR; PG8_SCHED;
;             PG8_STAGE(PG8_SB(0, 1), b2 + hstepB, voffB);
;             PG8_WAIT_V(6); PG8_BAR; PG8_MMA(1, 1, At, B1); PG8_BAR;
;             PG8_LDB(B0, 1, 0); PG8_SCHED; PG8_LDA(At, 1, 0); PG8_STAGE(PG8_SA(0, 1), a2 + hstepA, voffA);
;             PG8_WAIT_L(8); PG8_BAR; PG8_WAIT_L(0); PG8_MMA(0, 0, At, B0); PG8_BAR; PG8_SCHED;
;             PG8_LDB(B1, 1, 1); PG8_STAGE(PG8_SB(1, 0), b3, voffB);
;             PG8_BAR; PG8_WAIT_L(0); PG8_MMA(0, 1, At, B1); PG8_BAR;
;             PG8_LDA(At, 1, 1); PG8_STAGE(PG8_SA(1, 0), a3, voffA);
;             PG8_BAR; PG8_WAIT_L(0); PG8_MMA(1, 0, At, B0); PG8_BAR; PG8_SCHED;
	s_setprio 1
	v_mfma_f32_16x16x32_bf16 v[48:51], v[218:221], v[186:189], v[48:51]
	v_mfma_f32_16x16x32_bf16 v[40:43], v[226:229], v[186:189], v[40:43]
	v_mfma_f32_16x16x32_bf16 v[32:35], v[218:221], v[194:197], v[32:35]
	v_mfma_f32_16x16x32_bf16 v[24:27], v[226:229], v[194:197], v[24:27]
	v_mfma_f32_16x16x32_bf16 v[16:19], v[218:221], v[202:205], v[16:19]
	v_mfma_f32_16x16x32_bf16 v[8:11], v[226:229], v[202:205], v[8:11]
	v_mfma_f32_16x16x32_bf16 v[4:7], v[218:221], v[210:213], v[4:7]
	v_mfma_f32_16x16x32_bf16 v[0:3], v[226:229], v[210:213], v[0:3]
	v_mfma_f32_16x16x32_bf16 v[48:51], v[222:225], v[190:193], v[48:51]
	v_mfma_f32_16x16x32_bf16 v[40:43], v[230:233], v[190:193], v[40:43]
	v_mfma_f32_16x16x32_bf16 v[32:35], v[222:225], v[198:201], v[32:35]
	v_mfma_f32_16x16x32_bf16 v[24:27], v[230:233], v[198:201], v[24:27]
	v_mfma_f32_16x16x32_bf16 v[16:19], v[222:225], v[206:209], v[16:19]
	v_mfma_f32_16x16x32_bf16 v[8:11], v[230:233], v[206:209], v[8:11]
	v_mfma_f32_16x16x32_bf16 v[4:7], v[222:225], v[214:217], v[4:7]
	v_mfma_f32_16x16x32_bf16 v[0:3], v[230:233], v[214:217], v[0:3]
	s_setprio 0
	s_add_i32 s69, 0, 0x18000
	v_add_u32_e32 v157, s69, v153
	s_barrier
	ds_read_b128 v[158:161], v157
	ds_read_b128 v[174:177], v157 offset:1024
	ds_read_b128 v[178:181], v157 offset:2048
	ds_read_b128 v[182:185], v157 offset:3072
	s_add_u32 s46, s46, 0x100000
	s_addc_u32 s47, s47, 0
	s_mov_b32 m0, s54
	ds_read_b128 v[186:189], v155 offset:32768
	ds_read_b128 v[190:193], v155 offset:33792
	ds_read_b128 v[194:197], v155 offset:34816
	ds_read_b128 v[198:201], v155 offset:35840
	ds_read_b128 v[202:205], v155 offset:36864
	ds_read_b128 v[206:209], v155 offset:37888
	ds_read_b128 v[210:213], v155 offset:38912
	ds_read_b128 v[214:217], v155 offset:39936
	global_load_lds_dwordx4 v134, s[46:47]
	s_mov_b32 m0, s55
	s_nop 0
	global_load_lds_dwordx4 v138, s[46:47]
	s_waitcnt lgkmcnt(8)
	s_barrier
	s_waitcnt lgkmcnt(0)
	s_setprio 1
	s_waitcnt lgkmcnt(0)
	v_mfma_f32_16x16x32_bf16 v[124:127], v[158:161], v[186:189], v[124:127]
	v_mfma_f32_16x16x32_bf16 v[120:123], v[178:181], v[186:189], v[120:123]
	v_mfma_f32_16x16x32_bf16 v[112:115], v[158:161], v[194:197], v[112:115]
	v_mfma_f32_16x16x32_bf16 v[104:107], v[178:181], v[194:197], v[104:107]
	v_mfma_f32_16x16x32_bf16 v[100:103], v[158:161], v[202:205], v[100:103]
	v_mfma_f32_16x16x32_bf16 v[92:95], v[178:181], v[202:205], v[92:95]
	v_mfma_f32_16x16x32_bf16 v[84:87], v[158:161], v[210:213], v[84:87]
	v_mfma_f32_16x16x32_bf16 v[76:79], v[178:181], v[210:213], v[76:79]
	v_mfma_f32_16x16x32_bf16 v[124:127], v[174:177], v[190:193], v[124:127]
	v_mfma_f32_16x16x32_bf16 v[120:123], v[182:185], v[190:193], v[120:123]
	v_mfma_f32_16x16x32_bf16 v[112:115], v[174:177], v[198:201], v[112:115]
	v_mfma_f32_16x16x32_bf16 v[104:107], v[182:185], v[198:201], v[104:107]
	v_mfma_f32_16x16x32_bf16 v[100:103], v[174:177], v[206:209], v[100:103]
	v_mfma_f32_16x16x32_bf16 v[92:95], v[182:185], v[206:209], v[92:95]
	v_mfma_f32_16x16x32_bf16 v[84:87], v[174:177], v[214:217], v[84:87]
	v_mfma_f32_16x16x32_bf16 v[76:79], v[182:185], v[214:217], v[76:79]
	s_setprio 0
	s_barrier
	s_add_i32 s46, 0, 0x1c000
	s_add_i32 s47, s69, s49
	v_add_u32_e32 v157, s46, v153
	s_add_u32 s98, s36, s10
	s_addc_u32 s99, s37, s11
	s_mov_b32 m0, s47
	ds_read_b128 v[218:221], v157
	ds_read_b128 v[222:225], v157 offset:1024
	ds_read_b128 v[226:229], v157 offset:2048
	ds_read_b128 v[230:233], v157 offset:3072
	global_load_lds_dwordx4 v136, s[98:99]
	s_add_i32 m0, s47, 0x2000
	s_nop 0
	global_load_lds_dwordx4 v140, s[98:99]
	s_barrier
; #define PG8_STAGE(bufoff, gbase, voff) do { _Pragma("unroll") for (int _i = 0; _i < 2; ++_i) \
;         __builtin_amdgcn_global_load_lds((const unsigned*)((const char*)(gbase) + (voff)[_i]), (LAS unsigned*)(lds + (bufoff) + ldsw + _i * 8192), 16, 0, 0); } while (0)
; #define PG8_LDA(dst, b, h) do { _Pragma("unroll") for (int m = 0; m < 4; ++m) _Pragma("unroll") for (int k = 0; k < 2; ++k) dst[m][k] = *(const LAS bf16x8*)(lds + PG8_SA(b, h) + aoff + m * 2048 + k * 1024); } while (0)
; #define PG8_MMA(ai, bj, At, Bt) do { __builtin_amdgcn_s_setprio(1); _Pragma("unroll") for (int m = 0; m < 4; ++m) _Pragma("unroll") for (int n = 0; n < 2; ++n) _Pragma("unroll") for (int k = 0; k < 2; ++k) \
;         acc[ai][bj][m][n] = __builtin_amdgcn_mfma_f32_16x16x32_bf16(Bt[n][k], At[m][k], acc[ai][bj][m][n], 0, 0, 0); __builtin_amdgcn_s_setprio(0); } while (0)
; #define PG8_WAIT_V(n) asm volatile("s_waitcnt vmcnt(" #n ")" ::: "memory")
; #define PG8_WAIT_L(n) asm volatile("s_waitcnt lgkmcnt(" #n ")" ::: "memory")
; #define PG8_BAR __builtin_amdgcn_s_barrier()
; #define PG8_SCHED __builtin_amdgcn_sched_barrier(0)
;     __device__ __forceinline__ void operator()(const f32x4 (&acc)[2][2][4][2], const Unit& u, int wr, int wc, int fr, int fq) const {
;     ...
;         if (u.ocol < 6144) { const int sect = u.ocol >> 11, hh0 = (u.ocol & 2047) >> 7, b = u.orow >= SEQ ? 1 : 0;
;             base = qkv + (size_t)sect * MTOK * 2048 + ((size_t)(b * 16 + hh0) * SEQ + (row0 & (SEQ - 1))) * 128 + wc * 32 + 8 * fq; rstride = 128; bjstride = (size_t)SEQ * 128; }
;         else { base = proj2 + (size_t)row0 * NP2 + (u.ocol - 6144) + wc * 32 + 8 * fq; rstride = NP2; bjstride = HALF; }
; template <class Epi, class Job>
; __device__ __forceinline__ void gemm_phase(LAS unsigned char* lds, const Job& S, const Epi& E) {
;     ...
;             PG8_BAR; PG8_WAIT_L(0); PG8_MMA(0, 1, At, B1); PG8_BAR;
;             PG8_LDA(At, 1, 1); PG8_STAGE(PG8_SA(1, 0), a3, voffA);
;             PG8_BAR; PG8_WAIT_L(0); PG8_MMA(1, 0, At, B0); PG8_BAR; PG8_SCHED;
;             PG8_STAGE(PG8_SB(1, 1), b3 + hstepB, voffB);
;             PG8_WAIT_V(6); PG8_BAR; PG8_MMA(1, 1, At, B1); PG8_BAR;
;         }
	s_waitcnt lgkmcnt(0)
	s_setprio 1
	s_waitcnt lgkmcnt(0)
	v_mfma_f32_16x16x32_bf16 v[116:119], v[218:221], v[186:189], v[116:119]
	v_mfma_f32_16x16x32_bf16 v[108:111], v[226:229], v[186:189], v[108:111]
	v_mfma_f32_16x16x32_bf16 v[96:99], v[218:221], v[194:197], v[96:99]
	v_mfma_f32_16x16x32_bf16 v[88:91], v[226:229], v[194:197], v[88:91]
	v_mfma_f32_16x16x32_bf16 v[80:83], v[218:221], v[202:205], v[80:83]
	v_mfma_f32_16x16x32_bf16 v[72:75], v[226:229], v[202:205], v[72:75]
	v_mfma_f32_16x16x32_bf16 v[68:71], v[218:221], v[210:213], v[68:71]
	v_mfma_f32_16x16x32_bf16 v[64:67], v[226:229], v[210:213], v[64:67]
	v_mfma_f32_16x16x32_bf16 v[116:119], v[222:225], v[190:193], v[116:119]
	v_mfma_f32_16x16x32_bf16 v[108:111], v[230:233], v[190:193], v[108:111]
	v_mfma_f32_16x16x32_bf16 v[96:99], v[222:225], v[198:201], v[96:99]
	v_mfma_f32_16x16x32_bf16 v[88:91], v[230:233], v[198:201], v[88:91]
	v_mfma_f32_16x16x32_bf16 v[80:83], v[222:225], v[206:209], v[80:83]
	v_mfma_f32_16x16x32_bf16 v[72:75], v[230:233], v[206:209], v[72:75]
	v_mfma_f32_16x16x32_bf16 v[68:71], v[222:225], v[214:217], v[68:71]
	v_mfma_f32_16x16x32_bf16 v[64:67], v[230:233], v[214:217], v[64:67]
	s_setprio 0
	s_mov_b32 m0, s56
	s_add_u32 s100, s100, s10
	s_addc_u32 s101, s101, s11
	s_barrier
	ds_read_b128 v[186:189], v155 offset:49152
	ds_read_b128 v[190:193], v155 offset:50176
	ds_read_b128 v[194:197], v155 offset:51200
	ds_read_b128 v[198:201], v155 offset:52224
	ds_read_b128 v[202:205], v155 offset:53248
	ds_read_b128 v[206:209], v155 offset:54272
	ds_read_b128 v[210:213], v155 offset:55296
	ds_read_b128 v[214:217], v155 offset:56320
	global_load_lds_dwordx4 v134, s[100:101]
	s_mov_b32 m0, s57
	s_nop 0
	global_load_lds_dwordx4 v138, s[100:101]
	s_barrier
	s_waitcnt lgkmcnt(0)
	s_setprio 1
	s_waitcnt lgkmcnt(0)
	v_mfma_f32_16x16x32_bf16 v[60:63], v[158:161], v[186:189], v[60:63]
	v_mfma_f32_16x16x32_bf16 v[56:59], v[178:181], v[186:189], v[56:59]
	v_mfma_f32_16x16x32_bf16 v[52:55], v[158:161], v[194:197], v[52:55]
	v_mfma_f32_16x16x32_bf16 v[44:47], v[178:181], v[194:197], v[44:47]
	v_mfma_f32_16x16x32_bf16 v[36:39], v[158:161], v[202:205], v[36:39]
	v_mfma_f32_16x16x32_bf16 v[28:31], v[178:181], v[202:205], v[28:31]
	v_mfma_f32_16x16x32_bf16 v[20:23], v[158:161], v[210:213], v[20:23]
	v_mfma_f32_16x16x32_bf16 v[12:15], v[178:181], v[210:213], v[12:15]
	v_mfma_f32_16x16x32_bf16 v[60:63], v[174:177], v[190:193], v[60:63]
	v_mfma_f32_16x16x32_bf16 v[56:59], v[182:185], v[190:193], v[56:59]
	v_mfma_f32_16x16x32_bf16 v[52:55], v[174:177], v[198:201], v[52:55]
	v_mfma_f32_16x16x32_bf16 v[44:47], v[182:185], v[198:201], v[44:47]
	v_mfma_f32_16x16x32_bf16 v[36:39], v[174:177], v[206:209], v[36:39]
	v_mfma_f32_16x16x32_bf16 v[28:31], v[182:185], v[206:209], v[28:31]
	v_mfma_f32_16x16x32_bf16 v[20:23], v[174:177], v[214:217], v[20:23]
	v_mfma_f32_16x16x32_bf16 v[12:15], v[182:185], v[214:217], v[12:15]
	s_setprio 0
	s_barrier
	s_add_u32 s36, s36, 0x100080
	s_addc_u32 s37, s37, 0
	s_add_i32 s46, s46, s49
	s_mov_b32 m0, s46
	s_nop 0
	global_load_lds_dwordx4 v136, s[36:37]
	s_add_i32 m0, s46, 0x2000
	s_nop 0
	global_load_lds_dwordx4 v140, s[36:37]
	s_waitcnt vmcnt(6)
	s_barrier
	s_setprio 1
	v_mfma_f32_16x16x32_bf16 v[48:51], v[218:221], v[186:189], v[48:51]
	v_mfma_f32_16x16x32_bf16 v[40:43], v[226:229], v[186:189], v[40:43]
	v_mfma_f32_16x16x32_bf16 v[32:35], v[218:221], v[194:197], v[32:35]
	v_mfma_f32_16x16x32_bf16 v[24:27], v[226:229], v[194:197], v[24:27]
	v_mfma_f32_16x16x32_bf16 v[16:19], v[218:221], v[202:205], v[16:19]
	v_mfma_f32_16x16x32_bf16 v[8:11], v[226:229], v[202:205], v[8:11]
	v_mfma_f32_16x16x32_bf16 v[4:7], v[218:221], v[210:213], v[4:7]
	v_mfma_f32_16x16x32_bf16 v[0:3], v[226:229], v[210:213], v[0:3]
	v_mfma_f32_16x16x32_bf16 v[48:51], v[222:225], v[190:193], v[48:51]
	v_mfma_f32_16x16x32_bf16 v[40:43], v[230:233], v[190:193], v[40:43]
	v_mfma_f32_16x16x32_bf16 v[32:35], v[222:225], v[198:201], v[32:35]
	v_mfma_f32_16x16x32_bf16 v[24:27], v[230:233], v[198:201], v[24:27]
	v_mfma_f32_16x16x32_bf16 v[16:19], v[222:225], v[206:209], v[16:19]
	v_mfma_f32_16x16x32_bf16 v[8:11], v[230:233], v[206:209], v[8:11]
	v_mfma_f32_16x16x32_bf16 v[4:7], v[222:225], v[214:217], v[4:7]
	v_mfma_f32_16x16x32_bf16 v[0:3], v[230:233], v[214:217], v[0:3]
	s_setprio 0
	s_add_i32 s68, s68, 2
	s_add_u32 s28, s28, 0x100
	s_addc_u32 s29, s29, 0
	s_add_u32 s27, s27, 0x100
	s_addc_u32 s67, s67, 0
	s_cmp_gt_u32 s68, 61
	s_barrier
	s_cbranch_scc0 .LBB0_186
	v_add_u32_e32 v157, s66, v131
	s_cmpk_gt_i32 s26, 0x17ff
	s_mov_b64 s[28:29], -1
	s_cbranch_scc0 .LBB0_189
	v_mov_b64_e32 v[150:151], s[20:21]
	v_mad_i64_i32 v[150:151], s[28:29], v157, s62, v[150:151]
	s_mov_b32 s27, s9
	v_lshl_add_u64 v[150:151], s[26:27], 1, v[150:151]
	v_lshl_add_u64 v[150:151], v[150:151], 0, s[12:13]
	s_mov_b64 s[28:29], 0

; __device__ __forceinline__ void attn_passes(const Params& p, LAS unsigned char* lds) {
;     ...
;     const int nk = ((int)blockIdx.x < 256) ? (256 - (int)blockIdx.x + G - 1) / G : 0, nunits = 6 * nk;
; __device__ __forceinline__ void p3_pool(const Params& p) {
;     const bf16_t* proj = (const bf16_t*)(p.ws + WS_PROJ2); bf16_t* ycat = (bf16_t*)(p.ws + WS_YCAT);
;     const int tid = threadIdx.x, cch = tid & 255, sub = tid >> 8, j0 = cch * 8;
;     const int w = 2 << (j0 >> 9);
;     float ps[8];
;     { const f32x4 a = *(const f32x4*)(p.pool_scale + j0), b = *(const f32x4*)(p.pool_scale + j0 + 4); ps[0] = a[0]; ps[1] = a[1]; ps[2] = a[2]; ps[3] = a[3]; ps[4] = b[0]; ps[5] = b[1]; ps[6] = b[2]; ps[7] = b[3]; }
;     for (int item = blockIdx.x; item < 256; item += gridDim.x) {
;         const int t0 = item * 64 + sub * 32, pos0 = t0 & (SEQ - 1);
.LBB0_248:
	s_cmp_lt_i32 s37, 1
	s_cbranch_scc1 .LBB0_316
	s_cmpk_gt_u32 s2, 0xff
	s_cbranch_scc1 .Lpq_skip
	s_bitcmp1_b32 s2, 0
	s_cbranch_scc0 .Lpq_skip
	v_writelane_b32 v238, s4, 0
	v_writelane_b32 v238, s5, 1
	v_writelane_b32 v238, s6, 2
	v_writelane_b32 v238, s7, 3
	v_writelane_b32 v238, s8, 4
	v_writelane_b32 v238, s9, 5
	v_writelane_b32 v238, s10, 6
	v_writelane_b32 v238, s11, 7
	v_writelane_b32 v238, s12, 8
	v_writelane_b32 v238, s13, 9
	v_writelane_b32 v238, s22, 10
	v_writelane_b32 v238, s23, 11
	v_and_b32_e32 v34, 0x7f8, v172
	v_lshlrev_b32_e32 v8, 2, v34
	global_load_dwordx4 v[0:3], v8, s[30:31]
	global_load_dwordx4 v[4:7], v8, s[30:31] offset:16
	v_lshrrev_b32_e32 v24, 9, v34
	v_lshlrev_b32_e32 v16, 1, v34
	v_readfirstlane_b32 s100, v24
	v_readfirstlane_b32 s96, v173
	v_add_u32_e32 v17, 0x2000, v16
	v_add_u32_e32 v16, 0x1000, v16
	v_sub_u32_e32 v19, 126, v24
	v_lshlrev_b32_e32 v19, 23, v19
	s_nop 3
	s_lshl_b32 s100, 2, s100
	s_add_i32 s11, s100, -1
	s_mul_i32 s22, s11, 0x3000
	s_mov_b32 s12, s2
	s_waitcnt vmcnt(0)
